# phase-0 work queue: next item index prefetched (atomic issued one item ahead), no store drain at loop top
# speedup vs baseline: 1.0022x; 1.0022x over previous
.LBB0_771:
	s_andn2_b64 vcc, exec, s[2:3]
	v_readlane_b32 s10, v254, 41
	s_cbranch_vccnz .LBB0_8
	v_readlane_b32 s10, v255, 28
	v_readlane_b32 s11, v255, 29
	s_add_u32 s2, s10, 0x2b274000
	s_addc_u32 s3, s11, 0
	s_add_u32 s0, s10, 0x28674000
	s_addc_u32 s1, s11, 0
	s_add_u32 s20, s10, 0x1e34000
	s_addc_u32 s21, s11, 0
	s_add_u32 s4, s10, 0x1634000
	s_addc_u32 s5, s11, 0
	s_add_u32 s6, s10, 0xa34000
	s_addc_u32 s7, s11, 0
	s_add_u32 s8, s10, 0x234000
	s_addc_u32 s9, s11, 0
	v_mov_b32_e32 v56, v179
	s_add_u32 s10, s10, 0x7a34000
	s_mov_b32 s54, 0xc09de9e6
	s_mov_b32 s52, 0x4081e0d3
	s_mov_b32 s50, 0xbfaad1da
	s_mov_b32 s48, 0x3d4be544
	s_mov_b32 s46, 0x40490fdb
	s_mov_b32 s38, 0xc0a55e0e
	s_mov_b32 s34, 0x40234736
	s_addc_u32 s11, s11, 0
	v_mov_b32_e32 v60, v56
	v_cmp_eq_u32_e64 s[42:43], 0, v56
	s_and_saveexec_b64 s[12:13], s[42:43]
	s_cbranch_execz .Lq_pre_done
	v_mov_b32_e32 v250, 1
	global_atomic_add v250, v177, v250, s[2:3] sc0
	s_waitcnt vmcnt(0)
.Lq_pre_done:
	s_or_b64 exec, exec, s[12:13]
	s_branch .LBB0_776

.LBB0_776:
	s_waitcnt lgkmcnt(0)
	s_barrier
	s_and_saveexec_b64 s[12:13], s[42:43]
	s_cbranch_execz .LBB0_780
	v_readlane_b32 s14, v254, 36
	s_waitcnt vmcnt(4)
	v_mov_b32_e32 v0, v250
	v_mov_b32_e32 v1, s14
	ds_write_b32 v1, v0
	v_mov_b32_e32 v250, 1
	global_atomic_add v250, v177, v250, s[2:3] sc0
